# attention: the next unit's query rows are prefetched into spare registers during the last key-pair step of the current unit (unit start no longer waits on a global load)
# speedup vs baseline: 1.0053x; 1.0037x over previous
.LBB0_1067:
	s_or_b64 exec, exec, s[4:5]
	s_ashr_i32 s4, s16, 6
	s_lshl_b32 s5, s4, 5
	s_mulk_i32 s4, 0x1200
	s_add_i32 s4, s4, 0
	s_add_i32 s12, s4, 0x16000
	s_add_i32 s4, 0, 0x20400
	v_ashrrev_i32_e32 v2, 3, v5
	v_mov_b32_e32 v5, s4
	s_lshl_b32 s4, s17, 12
	v_and_b32_e32 v3, 31, v4
	s_and_b32 s13, s4, 0x7000
	v_and_or_b32 v6, s5, 32, v3
	v_and_b32_e32 v1, 3, v4
	s_movk_i32 s5, 0xc20
	v_sub_co_u32_e32 v8, vcc, s13, v3
	v_mad_u32_u24 v5, v1, s5, v5
	s_nop 0
	v_subb_co_u32_e64 v9, s[4:5], 0, 0, vcc
	v_lshrrev_b32_e32 v14, 5, v0
	v_sub_u32_e32 v1, v1, v6
	s_lshl_b32 s4, s18, 6
	v_lshlrev_b32_e32 v1, 2, v1
	v_lshlrev_b32_e32 v15, 4, v14
	v_mov_b32_e32 v7, 0
	s_ashr_i32 s5, s4, 31
	s_and_b32 s14, s17, 8
	s_ashr_i32 s15, s16, 7
	v_add3_u32 v133, v5, v1, v15
	v_lshrrev_b32_e32 v0, 3, v0
	v_mov_b32_e32 v1, v7
	s_lshl_b64 s[4:5], s[4:5], 1
	v_lshl_add_u64 v[8:9], v[8:9], 0, v[0:1]
	s_add_u32 s6, s8, s4
	v_lshlrev_b32_e32 v1, 4, v4
	v_lshl_add_u64 v[8:9], v[8:9], 0, v[6:7]
	s_addc_u32 s7, s9, s5
	v_and_b32_e32 v6, 0x70, v1
	v_lshl_add_u64 v[10:11], s[6:7], 0, v[6:7]
	s_lshl_b32 s7, s13, 11
	s_add_u32 s7, s8, s7
	s_movk_i32 s6, 0x90
	v_mov_b32_e32 v1, s12
	s_addc_u32 s8, s9, 0
	v_mul_u32_u24_e32 v16, 0x90, v3
	s_waitcnt vmcnt(0)
	v_mad_u32_u24 v17, v3, s6, v1
	v_ashrrev_i32_e32 v3, 31, v2
	s_add_u32 s4, s7, s4
	v_lshlrev_b64 v[12:13], 11, v[2:3]
	s_addc_u32 s5, s8, s5
	v_lshl_add_u64 v[12:13], s[4:5], 0, v[12:13]
	v_lshl_add_u64 v[12:13], v[12:13], 0, v[6:7]
	s_mov_b64 s[4:5], 0x4800000
	v_mul_lo_u32 v1, v2, s6
	v_lshl_add_u64 v[128:129], v[12:13], 0, s[4:5]
	s_mov_b64 s[4:5], 0x8800000
	v_add3_u32 v132, 0, v1, v6
	v_lshl_add_u64 v[130:131], v[12:13], 0, s[4:5]
	v_mad_u64_u32 v[134:135], s[4:5], v2, 48, v[132:133]
	v_lshrrev_b32_e32 v1, 3, v4
	v_bfe_u32 v2, v4, 2, 2
	v_and_or_b32 v1, v1, 4, v2
	v_and_b32_e32 v2, 16, v4
	v_lshlrev_b32_e32 v4, 2, v4
	v_and_or_b32 v2, v4, 12, v2
	v_mul_u32_u24_e32 v1, 0xc0, v1
	v_lshlrev_b32_e32 v2, 1, v2
	v_add3_u32 v135, 0, v1, v2
	v_mul_u32_u24_e32 v2, 0x90, v0
	v_lshlrev_b64 v[0:1], 11, v[8:9]
	v_lshl_add_u64 v[0:1], v[10:11], 0, v[0:1]
	s_mov_b64 s[4:5], 0xc800000
	v_lshl_add_u64 v[136:137], v[0:1], 0, s[4:5]
	s_bfe_u32 s4, s17, 0x10003
	s_lshl_b32 s5, s4, 5
	s_add_i32 s17, s15, s5
	s_lshl_b32 s5, s15, 6
	s_lshl_b32 s4, s4, 11
	v_add_u32_e32 v5, s12, v6
	v_lshlrev_b32_e32 v3, 3, v14
	s_add_i32 s5, s5, s4
	s_mov_b32 s16, 0
	v_add3_u32 v174, 0, v16, v15
	s_sub_i32 s18, 0, s5
	v_add_u32_e32 v175, v5, v2
	s_mov_b64 s[4:5], 0x4000
	s_movk_i32 s19, 0x4000
	s_mov_b64 s[6:7], 0x8000
	s_mov_b64 s[8:9], 0xc000
	s_mov_b64 s[30:31], 0x80000
	v_add_u32_e32 v176, v17, v15
	v_add_u32_e32 v177, v17, v3
	s_waitcnt lgkmcnt(0)
	s_barrier
	s_branch .LBB0_1070

.LBB0_1069:
	v_mov_b32_e32 v38, v178
	s_nop 1
	v_permlane32_swap_b32_e32 v178, v38
	v_add_f32_e32 v38, v178, v38
	v_div_scale_f32 v39, s[12:13], v38, v38, 1.0
	v_rcp_f32_e32 v40, v39
	s_add_i32 s16, s16, 1
	s_add_i32 s17, s17, 4
	s_addk_i32 s18, 0xff00
	v_fma_f32 v41, -v39, v40, 1.0
	v_fmac_f32_e32 v40, v41, v40
	v_div_scale_f32 v41, vcc, 1.0, v38, 1.0
	v_mul_f32_e32 v42, v41, v40
	v_fma_f32 v43, -v39, v42, v41
	v_fmac_f32_e32 v42, v43, v40
	v_fma_f32 v39, -v39, v42, v41
	v_div_fmas_f32 v39, v39, v40, v42
	v_div_fixup_f32 v38, v39, v38, 1.0
	v_pk_mul_f32 v[0:1], v[0:1], v[38:39] op_sel_hi:[1,0]
	v_pk_mul_f32 v[2:3], v[2:3], v[38:39] op_sel_hi:[1,0]
	v_pk_mul_f32 v[4:5], v[4:5], v[38:39] op_sel_hi:[1,0]
	v_pk_mul_f32 v[6:7], v[6:7], v[38:39] op_sel_hi:[1,0]
	v_cvt_pk_bf16_f32 v0, v0, v1
	v_cvt_pk_bf16_f32 v1, v2, v3
	v_cvt_pk_bf16_f32 v4, v4, v5
	v_cvt_pk_bf16_f32 v5, v6, v7
	v_pk_mul_f32 v[2:3], v[16:17], v[38:39] op_sel_hi:[1,0]
	v_pk_mul_f32 v[16:17], v[18:19], v[38:39] op_sel_hi:[1,0]
	ds_write2_b64 v177, v[0:1], v[4:5] offset1:2
	v_pk_mul_f32 v[0:1], v[20:21], v[38:39] op_sel_hi:[1,0]
	v_pk_mul_f32 v[4:5], v[22:23], v[38:39] op_sel_hi:[1,0]
	v_cvt_pk_bf16_f32 v2, v2, v3
	v_cvt_pk_bf16_f32 v3, v16, v17
	v_cvt_pk_bf16_f32 v0, v0, v1
	v_cvt_pk_bf16_f32 v1, v4, v5
	ds_write2_b64 v177, v[2:3], v[0:1] offset0:8 offset1:10
	v_pk_mul_f32 v[0:1], v[8:9], v[38:39] op_sel_hi:[1,0]
	v_pk_mul_f32 v[2:3], v[10:11], v[38:39] op_sel_hi:[1,0]
	v_cvt_pk_bf16_f32 v0, v0, v1
	v_cvt_pk_bf16_f32 v1, v2, v3
	v_pk_mul_f32 v[2:3], v[24:25], v[38:39] op_sel_hi:[1,0]
	v_pk_mul_f32 v[4:5], v[26:27], v[38:39] op_sel_hi:[1,0]
	v_cvt_pk_bf16_f32 v2, v2, v3
	v_cvt_pk_bf16_f32 v3, v4, v5
	v_pk_mul_f32 v[4:5], v[12:13], v[38:39] op_sel_hi:[1,0]
	v_pk_mul_f32 v[6:7], v[14:15], v[38:39] op_sel_hi:[1,0]
	v_cvt_pk_bf16_f32 v4, v4, v5
	v_cvt_pk_bf16_f32 v5, v6, v7
	ds_write2_b64 v177, v[0:1], v[4:5] offset0:4 offset1:6
	v_pk_mul_f32 v[0:1], v[28:29], v[38:39] op_sel_hi:[1,0]
	v_pk_mul_f32 v[4:5], v[30:31], v[38:39] op_sel_hi:[1,0]
	v_cvt_pk_bf16_f32 v0, v0, v1
	v_cvt_pk_bf16_f32 v1, v4, v5
	ds_write2_b64 v177, v[2:3], v[0:1] offset0:12 offset1:14
	ds_read_b128 v[0:3], v175
	ds_read_b128 v[4:7], v175 offset:1152
	ds_read_b128 v[8:11], v175 offset:2304
	ds_read_b128 v[12:15], v175 offset:3456
	s_cmp_eq_u32 s16, 8
	v_lshl_add_u64 v[32:33], v[138:139], 0, s[4:5]
	v_lshl_add_u64 v[34:35], v[138:139], 0, s[6:7]
	v_lshl_add_u64 v[36:37], v[138:139], 0, s[8:9]
	s_waitcnt vmcnt(0) lgkmcnt(3)
	global_store_dwordx4 v[138:139], v[0:3], off
	s_waitcnt lgkmcnt(2)
	global_store_dwordx4 v[32:33], v[4:7], off
	s_waitcnt lgkmcnt(1)
	global_store_dwordx4 v[34:35], v[8:11], off
	s_waitcnt lgkmcnt(0)
	global_store_dwordx4 v[36:37], v[12:15], off
	s_barrier
	s_cbranch_scc1 .LBB0_1075
.LBB0_1070:
	s_or_b32 s12, s16, s14
	s_lshl_b32 s13, s12, 2
	s_add_i32 s20, s13, s15
	s_add_i32 s21, s13, -8
	s_cmp_gt_u32 s12, 1
	s_cselect_b32 s12, s21, 0
	s_ashr_i32 s21, s20, 31
	s_lshl_b64 s[20:21], s[20:21], 17
	v_lshl_add_u64 v[138:139], v[136:137], 0, s[20:21]
	s_cmp_lg_u32 s16, 0
	s_cbranch_scc1 .Lqpf_unit
	v_add_co_u32_e32 v8, vcc, s19, v138
	s_sub_i32 s13, s13, s12
	s_nop 0
	v_addc_co_u32_e32 v9, vcc, 0, v139, vcc
	global_load_dwordx4 v[0:3], v[138:139], off
	global_load_dwordx4 v[4:7], v[8:9], off
	v_add_co_u32_e32 v8, vcc, 0x8000, v138
	s_add_i32 s13, s13, 4
	s_nop 0
	v_addc_co_u32_e32 v9, vcc, 0, v139, vcc
	v_add_co_u32_e32 v12, vcc, 0xc000, v138
	global_load_dwordx4 v[8:11], v[8:9], off
	s_nop 0
	v_addc_co_u32_e32 v13, vcc, 0, v139, vcc
	global_load_dwordx4 v[12:15], v[12:13], off
	s_ashr_i32 s20, s13, 1
	s_cmp_lt_i32 s20, 1
	s_cbranch_scc1 .Latt_slow
	s_or_b32 s22, s12, 1
	s_ashr_i32 s23, s22, 31
	s_lshl_b64 s[22:23], s[22:23], 17
	s_ashr_i32 s13, s12, 31
	v_lshl_add_u64 v[32:33], v[130:131], 0, s[22:23]
	v_lshl_add_u64 v[34:35], v[128:129], 0, s[22:23]
	s_lshl_b64 s[22:23], s[12:13], 17
	global_load_dwordx4 v[112:115], v[32:33], off
	global_load_dwordx4 v[116:119], v[34:35], off
	v_lshl_add_u64 v[32:33], v[130:131], 0, s[22:23]
	v_lshl_add_u64 v[34:35], v[128:129], 0, s[22:23]
	global_load_dwordx4 v[120:123], v[32:33], off
	global_load_dwordx4 v[124:127], v[34:35], off
	s_waitcnt vmcnt(7)
	ds_write_b128 v175, v[0:3]
	s_waitcnt vmcnt(6)
	ds_write_b128 v175, v[4:7] offset:1152
	s_waitcnt vmcnt(5)
	ds_write_b128 v175, v[8:11] offset:2304
	s_waitcnt vmcnt(4)
	ds_write_b128 v175, v[12:15] offset:3456
	s_branch .Latt_join
.Lqpf_unit:
	s_sub_i32 s13, s13, s12
	s_add_i32 s13, s13, 4
	s_ashr_i32 s20, s13, 1
	s_or_b32 s22, s12, 1
	s_ashr_i32 s23, s22, 31
	s_lshl_b64 s[22:23], s[22:23], 17
	s_ashr_i32 s13, s12, 31
	v_lshl_add_u64 v[32:33], v[130:131], 0, s[22:23]
	v_lshl_add_u64 v[34:35], v[128:129], 0, s[22:23]
	s_lshl_b64 s[22:23], s[12:13], 17
	global_load_dwordx4 v[112:115], v[32:33], off
	global_load_dwordx4 v[116:119], v[34:35], off
	v_lshl_add_u64 v[32:33], v[130:131], 0, s[22:23]
	v_lshl_add_u64 v[34:35], v[128:129], 0, s[22:23]
	global_load_dwordx4 v[120:123], v[32:33], off
	global_load_dwordx4 v[124:127], v[34:35], off
	ds_write_b128 v175, v[220:223]
	ds_write_b128 v175, v[224:227] offset:1152
	ds_write_b128 v175, v[228:231] offset:2304
	ds_write_b128 v175, v[232:235] offset:3456
	s_branch .Latt_join

.LBB0_1073:
	s_mov_b32 s26, s23
	s_and_b32 s24, s22, 0x80
	s_add_i32 s23, s23, 1
	s_cmp_lt_i32 s23, s20
	s_cselect_b32 s26, s23, s26
	s_lshl_b32 s26, s26, 1
	s_add_i32 s26, s26, s12
	s_ashr_i32 s27, s26, 31
	s_mul_i32 s25, s24, 0x90
	s_mulk_i32 s24, 0xc0
	s_lshl_b64 s[28:29], s[26:27], 17
	s_or_b32 s26, s26, 1
	v_add_u32_e32 v32, s25, v132
	v_add_u32_e32 v33, s24, v134
	s_ashr_i32 s27, s26, 31
	s_waitcnt vmcnt(0)
	ds_write_b128 v32, v[124:127]
	ds_write_b128 v33, v[120:123] offset:36864
	ds_write_b128 v32, v[116:119] offset:9216
	ds_write_b128 v33, v[112:115] offset:49152
	v_lshl_add_u64 v[32:33], v[128:129], 0, s[28:29]
	s_lshl_b64 s[26:27], s[26:27], 17
	v_lshl_add_u64 v[34:35], v[130:131], 0, s[28:29]
	global_load_dwordx4 v[124:127], v[32:33], off
	global_load_dwordx4 v[120:123], v[34:35], off
	v_lshl_add_u64 v[32:33], v[128:129], 0, s[26:27]
	v_lshl_add_u64 v[34:35], v[130:131], 0, s[26:27]
	global_load_dwordx4 v[116:119], v[32:33], off
	global_load_dwordx4 v[112:115], v[34:35], off
	s_cmp_lg_u32 s23, s20
	s_cbranch_scc1 .Lqpf_skip
	s_cmp_eq_u32 s16, 7
	s_cbranch_scc1 .Lqpf_skip
	v_lshl_add_u64 v[218:219], v[138:139], 0, s[30:31]
	v_lshl_add_u64 v[236:237], v[218:219], 0, s[4:5]
	v_lshl_add_u64 v[238:239], v[218:219], 0, s[6:7]
	v_lshl_add_u64 v[240:241], v[218:219], 0, s[8:9]
	global_load_dwordx4 v[220:223], v[218:219], off
	global_load_dwordx4 v[224:227], v[236:237], off
	global_load_dwordx4 v[228:231], v[238:239], off
	global_load_dwordx4 v[232:235], v[240:241], off
.Lqpf_skip:
	s_cmp_gt_u32 s13, 9
	s_waitcnt lgkmcnt(0)
	s_barrier
	s_cbranch_scc1 .LBB0_1072
	s_add_i32 s26, s21, s22
	s_cmp_lg_u32 s13, 9
	s_cselect_b32 s27, s26, 0xfffffd80
	v_add_u32_e32 v152, s25, v174
	v_lshl_add_u32 v44, s27, 2, v133
	ds_read_b128 v[32:35], v152
	ds_read_b128 v[64:67], v44 offset:2816
	ds_read_b128 v[68:71], v44 offset:2848
	ds_read_b128 v[72:75], v44 offset:2880
	ds_read_b128 v[76:79], v44 offset:2912
	ds_read_b128 v[36:39], v152 offset:4608
	ds_read_b128 v[40:43], v152 offset:32
	s_waitcnt lgkmcnt(2)
	v_mfma_f32_32x32x16_bf16 v[64:79], v[32:35], v[96:99], v[64:79]
	ds_read_b128 v[80:83], v44 offset:2944
	ds_read_b128 v[84:87], v44 offset:2976
	ds_read_b128 v[88:91], v44 offset:3008
	ds_read_b128 v[92:95], v44 offset:3040
	ds_read_b128 v[32:35], v152 offset:4640
	s_add_i32 s26, s26, 64
	s_cmp_lg_u32 s13, 0
	s_cselect_b32 s25, s26, 0xfffffd80
	v_lshl_add_u32 v60, s25, 2, v133
	v_add_u32_e32 v179, s24, v135
	s_waitcnt lgkmcnt(1)
	v_mfma_f32_32x32x16_bf16 v[80:95], v[36:39], v[96:99], v[80:95]
	v_mfma_f32_32x32x16_bf16 v[64:79], v[40:43], v[100:103], v[64:79]
	s_waitcnt lgkmcnt(0)
	v_mfma_f32_32x32x16_bf16 v[80:95], v[32:35], v[100:103], v[80:95]
	ds_read_b128 v[32:35], v152 offset:64
	ds_read_b128 v[36:39], v152 offset:96
	s_waitcnt lgkmcnt(1)
	v_mfma_f32_32x32x16_bf16 v[64:79], v[32:35], v[104:107], v[64:79]
	ds_read_b128 v[32:35], v152 offset:4672
	ds_read_b128 v[48:51], v152 offset:4704
	s_waitcnt lgkmcnt(1)
	v_mfma_f32_32x32x16_bf16 v[80:95], v[32:35], v[104:107], v[80:95]
	v_mfma_f32_32x32x16_bf16 v[64:79], v[36:39], v[108:111], v[64:79]
	ds_read_b128 v[32:35], v60 offset:2816
	ds_read_b128 v[36:39], v60 offset:2848
	ds_read_b128 v[40:43], v60 offset:2880
	ds_read_b128 v[44:47], v60 offset:2912
	ds_read_b128 v[140:143], v152 offset:9216
	s_nop 6
	v_exp_f32_e32 v168, v64
	s_waitcnt lgkmcnt(5)
	v_mfma_f32_32x32x16_bf16 v[80:95], v[48:51], v[108:111], v[80:95]
	ds_read_b128 v[48:51], v60 offset:2944
	ds_read_b128 v[52:55], v60 offset:2976
	ds_read_b128 v[56:59], v60 offset:3008
	ds_read_b128 v[60:63], v60 offset:3040
	ds_read_b128 v[144:147], v152 offset:9248
	ds_read_b128 v[148:151], v152 offset:13824
	ds_read_b128 v[180:183], v152 offset:13856
	ds_read_b128 v[184:187], v152 offset:9280
	ds_read_b128 v[188:191], v152 offset:9312
	ds_read_b128 v[192:195], v152 offset:13888
	ds_read_b128 v[196:199], v152 offset:13920
	v_exp_f32_e32 v156, v65
	v_exp_f32_e32 v158, v66
	v_exp_f32_e32 v162, v67
	v_exp_f32_e32 v216, v68
	v_exp_f32_e32 v76, v76
	s_waitcnt lgkmcnt(5)
	v_mfma_f32_32x32x16_bf16 v[48:63], v[148:151], v[96:99], v[48:63]
	v_exp_f32_e32 v148, v71
	v_exp_f32_e32 v170, v80
	v_exp_f32_e32 v164, v82
	v_exp_f32_e32 v150, v86
	v_exp_f32_e32 v80, v72
	v_exp_f32_e32 v82, v73
	v_exp_f32_e32 v86, v74
	s_waitcnt lgkmcnt(4)
	v_mfma_f32_32x32x16_bf16 v[48:63], v[180:183], v[100:103], v[48:63]
	v_cvt_pk_bf16_f32 v180, v168, v156
	v_cvt_pk_bf16_f32 v181, v158, v162
	v_exp_f32_e32 v64, v77
	v_exp_f32_e32 v66, v78
	v_exp_f32_e32 v160, v81
	v_exp_f32_e32 v166, v83
	v_exp_f32_e32 v172, v84
	v_mfma_f32_32x32x16_bf16 v[32:47], v[140:143], v[96:99], v[32:47]
	v_exp_f32_e32 v140, v69
	v_exp_f32_e32 v142, v70
	v_exp_f32_e32 v70, v79
	v_exp_f32_e32 v154, v87
	v_cvt_pk_bf16_f32 v182, v216, v140
	v_cvt_pk_bf16_f32 v183, v142, v148
	v_exp_f32_e32 v84, v88
	s_waitcnt lgkmcnt(1)
	v_mfma_f32_32x32x16_bf16 v[48:63], v[192:195], v[104:107], v[48:63]
	ds_read_b64_tr_b16 v[192:193], v179 offset:36864
	ds_read_b64_tr_b16 v[194:195], v179 offset:38400
	ds_read_b64_tr_b16 v[202:203], v179 offset:38464
	ds_read_b64_tr_b16 v[200:201], v179 offset:36928
	v_exp_f32_e32 v88, v89
	v_exp_f32_e32 v152, v91
	v_exp_f32_e32 v92, v92
	v_exp_f32_e32 v68, v93
	v_exp_f32_e32 v72, v94
	v_mfma_f32_32x32x16_bf16 v[32:47], v[144:147], v[100:103], v[32:47]
	v_exp_f32_e32 v146, v90
	v_exp_f32_e32 v90, v75
	v_exp_f32_e32 v144, v85
	v_exp_f32_e32 v74, v95
	s_waitcnt lgkmcnt(0)
	v_mfma_f32_32x32x16_bf16 v[16:31], v[200:203], v[180:183], v[16:31]
	v_mfma_f32_32x32x16_bf16 v[0:15], v[192:195], v[180:183], v[0:15]
	ds_read_b64_tr_b16 v[192:193], v179 offset:39936
	ds_read_b64_tr_b16 v[194:195], v179 offset:41472
	ds_read_b64_tr_b16 v[206:207], v179 offset:41536
	ds_read_b64_tr_b16 v[204:205], v179 offset:40000
	ds_read_b64_tr_b16 v[208:209], v179 offset:43008
	ds_read_b64_tr_b16 v[210:211], v179 offset:44544
	ds_read_b64_tr_b16 v[214:215], v179 offset:44608
	ds_read_b64_tr_b16 v[212:213], v179 offset:43072
	ds_read_b64_tr_b16 v[180:181], v179 offset:46080
	ds_read_b64_tr_b16 v[182:183], v179 offset:47616
	ds_read_b64_tr_b16 v[202:203], v179 offset:47680
	ds_read_b64_tr_b16 v[200:201], v179 offset:46144
	v_mfma_f32_32x32x16_bf16 v[32:47], v[184:187], v[104:107], v[32:47]
	v_cvt_pk_bf16_f32 v184, v80, v82
	v_cvt_pk_bf16_f32 v185, v86, v90
	v_cvt_pk_bf16_f32 v186, v76, v64
	v_cvt_pk_bf16_f32 v187, v66, v70
	s_waitcnt lgkmcnt(8)
	s_nop 0
	v_mfma_f32_32x32x16_bf16 v[16:31], v[204:207], v[184:187], v[16:31]
	v_mfma_f32_32x32x16_bf16 v[0:15], v[192:195], v[184:187], v[0:15]
	v_mfma_f32_32x32x16_bf16 v[32:47], v[188:191], v[108:111], v[32:47]
	v_cvt_pk_bf16_f32 v188, v170, v160
	v_cvt_pk_bf16_f32 v189, v164, v166
	v_cvt_pk_bf16_f32 v190, v172, v144
	v_cvt_pk_bf16_f32 v191, v150, v154
	s_waitcnt lgkmcnt(4)
	s_nop 0
	v_mfma_f32_32x32x16_bf16 v[16:31], v[212:215], v[188:191], v[16:31]
	s_nop 4
	v_exp_f32_e32 v169, v32
	v_exp_f32_e32 v157, v33
	v_exp_f32_e32 v159, v34
	v_exp_f32_e32 v217, v36
	v_exp_f32_e32 v163, v35
	v_exp_f32_e32 v141, v37
	v_exp_f32_e32 v143, v38
	v_mfma_f32_32x32x16_bf16 v[0:15], v[208:211], v[188:191], v[0:15]
	v_exp_f32_e32 v149, v39
	v_exp_f32_e32 v81, v40
	v_exp_f32_e32 v83, v41
	v_exp_f32_e32 v87, v42
	v_exp_f32_e32 v91, v43
	ds_read_b64_tr_b16 v[40:41], v179 offset:49152
	ds_read_b64_tr_b16 v[42:43], v179 offset:50688
	v_cvt_pk_bf16_f32 v32, v169, v157
	v_mfma_f32_32x32x16_bf16 v[48:63], v[196:199], v[108:111], v[48:63]
	v_cvt_pk_bf16_f32 v196, v84, v88
	v_cvt_pk_bf16_f32 v197, v146, v152
	v_cvt_pk_bf16_f32 v198, v92, v68
	v_cvt_pk_bf16_f32 v199, v72, v74
	v_cvt_pk_bf16_f32 v33, v159, v163
	v_cvt_pk_bf16_f32 v34, v217, v141
	v_cvt_pk_bf16_f32 v35, v143, v149
	s_waitcnt lgkmcnt(2)
	v_mfma_f32_32x32x16_bf16 v[16:31], v[200:203], v[196:199], v[16:31]
	s_nop 2
	v_exp_f32_e32 v171, v48
	v_exp_f32_e32 v161, v49
	v_exp_f32_e32 v165, v50
	v_exp_f32_e32 v167, v51
	ds_read_b64_tr_b16 v[50:51], v179 offset:50752
	ds_read_b64_tr_b16 v[48:49], v179 offset:49216
	v_exp_f32_e32 v85, v56
	v_exp_f32_e32 v89, v57
	v_mfma_f32_32x32x16_bf16 v[0:15], v[180:183], v[196:199], v[0:15]
	v_add_f32_e64 v56, v168, v170
	v_add_f32_e64 v57, v169, v171
	v_exp_f32_e32 v173, v52
	v_exp_f32_e32 v145, v53
	v_exp_f32_e32 v151, v54
	v_exp_f32_e32 v155, v55
	v_exp_f32_e32 v77, v44
	v_exp_f32_e32 v65, v45
	s_waitcnt lgkmcnt(0)
	v_mfma_f32_32x32x16_bf16 v[16:31], v[48:51], v[32:35], v[16:31]
	v_exp_f32_e32 v67, v46
	v_exp_f32_e32 v71, v47
	ds_read_b64_tr_b16 v[52:53], v179 offset:52224
	ds_read_b64_tr_b16 v[54:55], v179 offset:53760
	v_cvt_pk_bf16_f32 v36, v81, v83
	v_cvt_pk_bf16_f32 v37, v87, v91
	v_cvt_pk_bf16_f32 v38, v77, v65
	v_cvt_pk_bf16_f32 v39, v67, v71
	v_mfma_f32_32x32x16_bf16 v[0:15], v[40:43], v[32:35], v[0:15]
	v_add_f32_e64 v32, v156, v160
	v_add_f32_e64 v33, v157, v161
	v_add_f32_e32 v56, v32, v56
	v_add_f32_e32 v57, v33, v57
	v_add_f32_e64 v48, v158, v164
	v_add_f32_e64 v49, v159, v165
	ds_read_b64_tr_b16 v[34:35], v179 offset:53824
	ds_read_b64_tr_b16 v[32:33], v179 offset:52288
	v_add_f32_e32 v50, v162, v166
	v_add_f32_e32 v51, v163, v167
	v_add_f32_e32 v48, v48, v56
	v_add_f32_e32 v49, v49, v57
	s_waitcnt lgkmcnt(0)
	v_mfma_f32_32x32x16_bf16 v[16:31], v[32:35], v[36:39], v[16:31]
	v_add_f32_e64 v78, v216, v172
	v_add_f32_e64 v79, v217, v173
	v_exp_f32_e32 v147, v58
	v_cvt_pk_bf16_f32 v44, v171, v161
	v_cvt_pk_bf16_f32 v45, v165, v167
	v_cvt_pk_bf16_f32 v46, v173, v145
	v_cvt_pk_bf16_f32 v47, v151, v155
	v_add_f32_e32 v56, v142, v150
	v_add_f32_e32 v57, v143, v151
	v_mfma_f32_32x32x16_bf16 v[0:15], v[52:55], v[36:39], v[0:15]
	v_add_f32_e64 v52, v50, v48
	v_add_f32_e64 v53, v51, v49
	ds_read_b64_tr_b16 v[48:49], v179 offset:55296
	ds_read_b64_tr_b16 v[50:51], v179 offset:56832
	ds_read_b64_tr_b16 v[34:35], v179 offset:56896
	ds_read_b64_tr_b16 v[32:33], v179 offset:55360
	v_add_f32_e32 v54, v140, v144
	v_add_f32_e32 v55, v141, v145
	v_add_f32_e32 v36, v78, v52
	v_add_f32_e32 v37, v79, v53
	v_exp_f32_e32 v153, v59
	v_add_f32_e32 v52, v54, v36
	v_add_f32_e32 v53, v55, v37
	v_add_f32_e32 v58, v148, v154
	v_add_f32_e32 v59, v149, v155
	s_waitcnt lgkmcnt(0)
	v_mfma_f32_32x32x16_bf16 v[16:31], v[32:35], v[44:47], v[16:31]
	v_add_f32_e64 v32, v56, v52
	v_add_f32_e64 v33, v57, v53
	v_exp_f32_e32 v93, v60
	v_exp_f32_e32 v69, v61
	v_add_f32_e32 v60, v80, v84
	v_add_f32_e32 v61, v81, v85
	v_add_f32_e32 v32, v58, v32
	v_add_f32_e32 v33, v59, v33
	v_exp_f32_e32 v73, v62
	v_exp_f32_e32 v75, v63
	v_mfma_f32_32x32x16_bf16 v[0:15], v[48:51], v[44:47], v[0:15]
	v_add_f32_e64 v62, v82, v88
	v_add_f32_e64 v63, v83, v89
	v_add_f32_e64 v32, v60, v32
	v_add_f32_e64 v33, v61, v33
	v_add_f32_e64 v80, v86, v146
	v_add_f32_e64 v81, v87, v147
	v_add_f32_e32 v32, v62, v32
	v_add_f32_e32 v33, v63, v33
	ds_read_b64_tr_b16 v[36:37], v179 offset:58368
	ds_read_b64_tr_b16 v[38:39], v179 offset:59904
	v_add_f32_e32 v44, v80, v32
	v_add_f32_e32 v45, v81, v33
	ds_read_b64_tr_b16 v[34:35], v179 offset:59968
	ds_read_b64_tr_b16 v[32:33], v179 offset:58432
	v_cvt_pk_bf16_f32 v40, v85, v89
	v_cvt_pk_bf16_f32 v41, v147, v153
	v_cvt_pk_bf16_f32 v42, v93, v69
	v_cvt_pk_bf16_f32 v43, v73, v75
	v_add_f32_e32 v82, v90, v152
	v_add_f32_e32 v83, v91, v153
	v_add_f32_e32 v76, v76, v92
	v_add_f32_e32 v77, v77, v93
	s_waitcnt lgkmcnt(2)
	v_mfma_f32_32x32x16_bf16 v[0:15], v[36:39], v[40:43], v[0:15]
	v_add_f32_e64 v36, v82, v44
	v_add_f32_e64 v37, v83, v45
	v_add_f32_e64 v48, v64, v68
	v_add_f32_e64 v49, v65, v69
	v_add_f32_e64 v36, v76, v36
	v_add_f32_e64 v37, v77, v37
	v_add_f32_e32 v50, v66, v72
	v_add_f32_e32 v51, v67, v73
	v_add_f32_e32 v36, v48, v36
	v_add_f32_e32 v37, v49, v37
	v_add_f32_e32 v64, v70, v74
	v_add_f32_e32 v65, v71, v75
	v_add_f32_e32 v36, v50, v36
	v_add_f32_e32 v37, v51, v37
	s_waitcnt lgkmcnt(0)
	v_mfma_f32_32x32x16_bf16 v[16:31], v[32:35], v[40:43], v[16:31]
	v_add_f32_e64 v36, v64, v36
	v_add_f32_e64 v37, v65, v37
	v_add_f32_e32 v36, v178, v36
	v_add_f32_e32 v178, v36, v37
	s_branch .LBB0_1072
